# per-tile accumulator zeroing done with 64 v_mov_b64 instead of 127 v_mov_b32 in all 15 GEMM tile loops
# speedup vs baseline: 1.0098x; 1.0001x over previous
;     DI const char* a(const Unit& u) const { return (const char*)(A + (size_t)u.pm * BM * lda); }
;     DI const char* a(const Unit& u) const { return (const char*)(A + (size_t)u.pm * BM * 2048 + (u.pn >> 1) * 512); }
;     DI const char* a(const Unit& u) const { return (const char*)((u.pn < 12 ? A1 : A2) + (size_t)u.pm * BM * 512); }
; #define PG8_STAGE(bufoff, gbase, voff) do { _Pragma("unroll") for (int _i = 0; _i < 2; ++_i) \
;         __builtin_amdgcn_global_load_lds((const unsigned*)((const char*)(gbase) + (voff)[_i]), (LAS unsigned*)(lds + (bufoff) + ldsw + _i * 8192), 16, 0, 0); } while (0)
; #define PG8_LDA(dst, b, h) do { _Pragma("unroll") for (int m = 0; m < 4; ++m) _Pragma("unroll") for (int k = 0; k < 2; ++k) dst[m][k] = *(const LAS bf16x8*)(lds + PG8_SA(b, h) + aoff + m * 2048 + k * 1024); } while (0)
; #define PG8_LDB(dst, b, h) do { _Pragma("unroll") for (int n = 0; n < 2; ++n) _Pragma("unroll") for (int k = 0; k < 2; ++k) dst[n][k] = *(const LAS bf16x8*)(lds + PG8_SB(b, h) + boff + n * 2048 + k * 1024); } while (0)
; #define PG8_SCHED __builtin_amdgcn_sched_barrier(0)
; template <class Map, class Epi>
; DI void gemm_phase(LAS unsigned char* lds, const Map& MP, const Epi& E, const int nM, const int nN, const int K, const int lda, const int ldb) {
;     ...
;         const bool has_next = sched_next(ui + 1, nM, nN, G, cblk, nxt);
;         const char* nA = has_next ? MP.a(nxt) : cA; const char* nB = has_next ? MP.b(nxt) : cB;
;         for (int t = 0; t < nt; t += 2) {
;             const bool last = (t == nt - 2);
;             const char* a1 = cA + (size_t)(t + 1) * kstep;
;             const char* a2 = last ? nA : cA + (size_t)(t + 2) * kstep; const char* b2 = last ? nB : cB + (size_t)(t + 2) * kstep;
;             const char* a3 = a2 + kstep; const char* b3 = b2 + kstep;
;             PG8_LDB(B0, 0, 0); PG8_SCHED; PG8_LDA(At, 0, 0); PG8_STAGE(PG8_SA(1, 1), a1 + hstepA, voffA);
;     ...
;         for (int a = 0; a < 2; ++a)
; #pragma unroll
;             for (int b = 0; b < 2; ++b)
; #pragma unroll
;                 for (int m = 0; m < 4; ++m)
; #pragma unroll
;                     for (int n = 0; n < 2; ++n) acc[a][b][m][n] = (f32x4){0.f, 0.f, 0.f, 0.f};
.LBB1_228:
	s_ashr_i32 s17, s16, 31
	v_cmp_lt_i64_e32 vcc, s[18:19], v[156:157]
	s_lshl_b64 s[18:19], s[16:17], 20
	s_add_u32 s17, s31, s18
	s_addc_u32 s20, s33, s19
	s_lshl_b32 s18, s52, 8
	s_and_b32 s18, s18, 0xfffffe00
	s_ashr_i32 s19, s18, 31
	s_lshl_b64 s[18:19], s[18:19], 1
	s_add_u32 s18, s17, s18
	s_addc_u32 s19, s20, s19
	s_and_b64 s[20:21], vcc, exec
	s_cselect_b32 s17, s19, s27
	s_cselect_b32 s43, s18, s26
	s_ashr_i32 s20, s52, 1
	s_ashr_i32 s21, s20, 31
	s_lshl_b64 s[20:21], s[20:21], 19
	s_add_u32 s20, s6, s20
	s_addc_u32 s21, s7, s21
	s_lshl_b32 s28, s52, 18
	s_and_b32 s28, s28, 0x40000
	s_add_u32 s20, s20, s28
	s_addc_u32 s21, s21, 0
	s_and_b64 s[28:29], vcc, exec
	s_cselect_b32 s53, s21, s25
	s_cselect_b32 s54, s20, s24
	s_add_u32 s55, s24, 0x100
	s_addc_u32 s56, s25, 0
	s_add_u32 s24, s26, 0x80080
	v_mov_b32_e32 v0, 0
	s_addc_u32 s25, s27, 0
	s_mov_b32 s57, -2
	v_mov_b32_e32 v1, 0
	v_mov_b64_e32 v[2:3], 0
	v_mov_b64_e32 v[4:5], 0
	v_mov_b64_e32 v[6:7], 0
	v_mov_b64_e32 v[8:9], 0
	v_mov_b64_e32 v[10:11], 0
	v_mov_b64_e32 v[12:13], 0
	v_mov_b64_e32 v[14:15], 0
	v_mov_b64_e32 v[16:17], 0
	v_mov_b64_e32 v[18:19], 0
	v_mov_b64_e32 v[20:21], 0
	v_mov_b64_e32 v[22:23], 0
	v_mov_b64_e32 v[24:25], 0
	v_mov_b64_e32 v[26:27], 0
	v_mov_b64_e32 v[28:29], 0
	v_mov_b64_e32 v[30:31], 0
	v_mov_b64_e32 v[32:33], 0
	v_mov_b64_e32 v[34:35], 0
	v_mov_b64_e32 v[36:37], 0
	v_mov_b64_e32 v[38:39], 0
	v_mov_b64_e32 v[40:41], 0
	v_mov_b64_e32 v[42:43], 0
	v_mov_b64_e32 v[44:45], 0
	v_mov_b64_e32 v[46:47], 0
	v_mov_b64_e32 v[48:49], 0
	v_mov_b64_e32 v[50:51], 0
	v_mov_b64_e32 v[52:53], 0
	v_mov_b64_e32 v[54:55], 0
	v_mov_b64_e32 v[56:57], 0
	v_mov_b64_e32 v[58:59], 0
	v_mov_b64_e32 v[60:61], 0
	v_mov_b64_e32 v[62:63], 0
	v_mov_b64_e32 v[64:65], 0
	v_mov_b64_e32 v[66:67], 0
	v_mov_b64_e32 v[68:69], 0
	v_mov_b64_e32 v[70:71], 0
	v_mov_b64_e32 v[88:89], 0
	v_mov_b64_e32 v[90:91], 0
	v_mov_b64_e32 v[92:93], 0
	v_mov_b64_e32 v[94:95], 0
	v_mov_b64_e32 v[96:97], 0
	v_mov_b64_e32 v[98:99], 0
	v_mov_b64_e32 v[100:101], 0
	v_mov_b64_e32 v[102:103], 0
	v_mov_b64_e32 v[104:105], 0
	v_mov_b64_e32 v[106:107], 0
	v_mov_b64_e32 v[108:109], 0
	v_mov_b64_e32 v[110:111], 0
	v_mov_b64_e32 v[112:113], 0
	v_mov_b64_e32 v[114:115], 0
	v_mov_b64_e32 v[116:117], 0
	v_mov_b64_e32 v[118:119], 0
	v_mov_b64_e32 v[120:121], 0
	v_mov_b64_e32 v[122:123], 0
	v_mov_b64_e32 v[124:125], 0
	v_mov_b64_e32 v[126:127], 0
	v_mov_b64_e32 v[128:129], 0
	v_mov_b64_e32 v[130:131], 0
	v_mov_b64_e32 v[132:133], 0
	v_mov_b64_e32 v[134:135], 0
	v_mov_b64_e32 v[136:137], 0
	v_mov_b64_e32 v[138:139], 0
	v_mov_b64_e32 v[140:141], 0
	v_mov_b64_e32 v[142:143], 0
	ds_read_b128 v[72:75], v167
	ds_read_b128 v[76:79], v167 offset:1024
	ds_read_b128 v[80:83], v167 offset:2048
	ds_read_b128 v[84:87], v167 offset:3072

;     DI const char* a(const Unit& u) const { return (const char*)(A + (size_t)u.pm * BM * lda); }
;     DI const char* a(const Unit& u) const { return (const char*)(A + (size_t)u.pm * BM * 2048 + (u.pn >> 1) * 512); }
;     DI const char* a(const Unit& u) const { return (const char*)((u.pn < 12 ? A1 : A2) + (size_t)u.pm * BM * 512); }
; #define PG8_STAGE(bufoff, gbase, voff) do { _Pragma("unroll") for (int _i = 0; _i < 2; ++_i) \
;         __builtin_amdgcn_global_load_lds((const unsigned*)((const char*)(gbase) + (voff)[_i]), (LAS unsigned*)(lds + (bufoff) + ldsw + _i * 8192), 16, 0, 0); } while (0)
; #define PG8_LDA(dst, b, h) do { _Pragma("unroll") for (int m = 0; m < 4; ++m) _Pragma("unroll") for (int k = 0; k < 2; ++k) dst[m][k] = *(const LAS bf16x8*)(lds + PG8_SA(b, h) + aoff + m * 2048 + k * 1024); } while (0)
; #define PG8_LDB(dst, b, h) do { _Pragma("unroll") for (int n = 0; n < 2; ++n) _Pragma("unroll") for (int k = 0; k < 2; ++k) dst[n][k] = *(const LAS bf16x8*)(lds + PG8_SB(b, h) + boff + n * 2048 + k * 1024); } while (0)
; #define PG8_SCHED __builtin_amdgcn_sched_barrier(0)
; template <class Map, class Epi>
; DI void gemm_phase(LAS unsigned char* lds, const Map& MP, const Epi& E, const int nM, const int nN, const int K, const int lda, const int ldb) {
;     ...
;         const bool has_next = sched_next(ui + 1, nM, nN, G, cblk, nxt);
;         const char* nA = has_next ? MP.a(nxt) : cA; const char* nB = has_next ? MP.b(nxt) : cB;
;         for (int t = 0; t < nt; t += 2) {
;             const bool last = (t == nt - 2);
;             const char* a1 = cA + (size_t)(t + 1) * kstep;
;             const char* a2 = last ? nA : cA + (size_t)(t + 2) * kstep; const char* b2 = last ? nB : cB + (size_t)(t + 2) * kstep;
;             const char* a3 = a2 + kstep; const char* b3 = b2 + kstep;
;             PG8_LDB(B0, 0, 0); PG8_SCHED; PG8_LDA(At, 0, 0); PG8_STAGE(PG8_SA(1, 1), a1 + hstepA, voffA);
;     ...
;         for (int a = 0; a < 2; ++a)
; #pragma unroll
;             for (int b = 0; b < 2; ++b)
; #pragma unroll
;                 for (int m = 0; m < 4; ++m)
; #pragma unroll
;                     for (int n = 0; n < 2; ++n) acc[a][b][m][n] = (f32x4){0.f, 0.f, 0.f, 0.f};
.LBB1_379:
	s_ashr_i32 s23, s22, 31
	v_cmp_lt_i64_e32 vcc, s[24:25], v[180:181]
	s_lshl_b64 s[24:25], s[22:23], 20
	s_add_u32 s24, s31, s24
	s_addc_u32 s25, s34, s25
	s_and_b64 s[26:27], vcc, exec
	s_cselect_b32 s23, s25, s29
	s_cselect_b32 s61, s24, s28
	s_ashr_i32 s21, s20, 31
	s_lshl_b64 s[26:27], s[20:21], 20
	s_add_u32 s26, s35, s26
	s_addc_u32 s27, s36, s27
	s_and_b64 s[46:47], vcc, exec
	s_cselect_b32 s21, s27, s45
	s_cselect_b32 s58, s26, s44
	s_add_u32 s59, s44, 0x100
	s_addc_u32 vcc_lo, s45, 0
	s_add_u32 s44, s28, 0x80080
	v_mov_b32_e32 v0, 0
	s_addc_u32 s45, s29, 0
	s_mov_b32 vcc_hi, -2
	v_mov_b32_e32 v1, 0
	v_mov_b64_e32 v[2:3], 0
	v_mov_b64_e32 v[4:5], 0
	v_mov_b64_e32 v[6:7], 0
	v_mov_b64_e32 v[8:9], 0
	v_mov_b64_e32 v[10:11], 0
	v_mov_b64_e32 v[12:13], 0
	v_mov_b64_e32 v[14:15], 0
	v_mov_b64_e32 v[16:17], 0
	v_mov_b64_e32 v[18:19], 0
	v_mov_b64_e32 v[20:21], 0
	v_mov_b64_e32 v[22:23], 0
	v_mov_b64_e32 v[24:25], 0
	v_mov_b64_e32 v[26:27], 0
	v_mov_b64_e32 v[28:29], 0
	v_mov_b64_e32 v[30:31], 0
	v_mov_b64_e32 v[32:33], 0
	v_mov_b64_e32 v[34:35], 0
	v_mov_b64_e32 v[36:37], 0
	v_mov_b64_e32 v[38:39], 0
	v_mov_b64_e32 v[40:41], 0
	v_mov_b64_e32 v[42:43], 0
	v_mov_b64_e32 v[44:45], 0
	v_mov_b64_e32 v[46:47], 0
	v_mov_b64_e32 v[48:49], 0
	v_mov_b64_e32 v[50:51], 0
	v_mov_b64_e32 v[52:53], 0
	v_mov_b64_e32 v[54:55], 0
	v_mov_b64_e32 v[56:57], 0
	v_mov_b64_e32 v[58:59], 0
	v_mov_b64_e32 v[60:61], 0
	v_mov_b64_e32 v[62:63], 0
	v_mov_b64_e32 v[64:65], 0
	v_mov_b64_e32 v[66:67], 0
	v_mov_b64_e32 v[68:69], 0
	v_mov_b64_e32 v[70:71], 0
	v_mov_b64_e32 v[72:73], 0
	v_mov_b64_e32 v[74:75], 0
	v_mov_b64_e32 v[76:77], 0
	v_mov_b64_e32 v[78:79], 0
	v_mov_b64_e32 v[104:105], 0
	v_mov_b64_e32 v[106:107], 0
	v_mov_b64_e32 v[116:117], 0
	v_mov_b64_e32 v[118:119], 0
	v_mov_b64_e32 v[120:121], 0
	v_mov_b64_e32 v[122:123], 0
	v_mov_b64_e32 v[124:125], 0
	v_mov_b64_e32 v[126:127], 0
	v_mov_b64_e32 v[128:129], 0
	v_mov_b64_e32 v[130:131], 0
	v_mov_b64_e32 v[132:133], 0
	v_mov_b64_e32 v[134:135], 0
	v_mov_b64_e32 v[136:137], 0
	v_mov_b64_e32 v[138:139], 0
	v_mov_b64_e32 v[140:141], 0
	v_mov_b64_e32 v[142:143], 0
	v_mov_b64_e32 v[144:145], 0
	v_mov_b64_e32 v[146:147], 0
	v_mov_b64_e32 v[148:149], 0
	v_mov_b64_e32 v[150:151], 0
	v_mov_b64_e32 v[152:153], 0
	v_mov_b64_e32 v[154:155], 0
	v_mov_b64_e32 v[156:157], 0
	v_mov_b64_e32 v[158:159], 0
	ds_read_b128 v[80:83], v189
	ds_read_b128 v[84:87], v189 offset:1024
	ds_read_b128 v[88:91], v189 offset:2048
	ds_read_b128 v[92:95], v189 offset:3072

;     DI const char* a(const Unit& u) const { return (const char*)(A + (size_t)u.pm * BM * lda); }
;     DI const char* a(const Unit& u) const { return (const char*)(A + (size_t)u.pm * BM * 2048 + (u.pn >> 1) * 512); }
;     DI const char* a(const Unit& u) const { return (const char*)((u.pn < 12 ? A1 : A2) + (size_t)u.pm * BM * 512); }
; #define PG8_STAGE(bufoff, gbase, voff) do { _Pragma("unroll") for (int _i = 0; _i < 2; ++_i) \
;         __builtin_amdgcn_global_load_lds((const unsigned*)((const char*)(gbase) + (voff)[_i]), (LAS unsigned*)(lds + (bufoff) + ldsw + _i * 8192), 16, 0, 0); } while (0)
; #define PG8_LDA(dst, b, h) do { _Pragma("unroll") for (int m = 0; m < 4; ++m) _Pragma("unroll") for (int k = 0; k < 2; ++k) dst[m][k] = *(const LAS bf16x8*)(lds + PG8_SA(b, h) + aoff + m * 2048 + k * 1024); } while (0)
; #define PG8_LDB(dst, b, h) do { _Pragma("unroll") for (int n = 0; n < 2; ++n) _Pragma("unroll") for (int k = 0; k < 2; ++k) dst[n][k] = *(const LAS bf16x8*)(lds + PG8_SB(b, h) + boff + n * 2048 + k * 1024); } while (0)
; #define PG8_SCHED __builtin_amdgcn_sched_barrier(0)
; template <class Map, class Epi>
; DI void gemm_phase(LAS unsigned char* lds, const Map& MP, const Epi& E, const int nM, const int nN, const int K, const int lda, const int ldb) {
;     ...
;             const char* a1 = cA + (size_t)(t + 1) * kstep;
;             const char* a2 = last ? nA : cA + (size_t)(t + 2) * kstep; const char* b2 = last ? nB : cB + (size_t)(t + 2) * kstep;
;             const char* a3 = a2 + kstep; const char* b3 = b2 + kstep;
;             PG8_LDB(B0, 0, 0); PG8_SCHED; PG8_LDA(At, 0, 0); PG8_STAGE(PG8_SA(1, 1), a1 + hstepA, voffA);
;     ...
;         for (int a = 0; a < 2; ++a)
; #pragma unroll
;             for (int b = 0; b < 2; ++b)
; #pragma unroll
;                 for (int m = 0; m < 4; ++m)
; #pragma unroll
;                     for (int n = 0; n < 2; ++n) acc[a][b][m][n] = (f32x4){0.f, 0.f, 0.f, 0.f};
.LBB1_549:
	s_add_u32 s5, s10, 0x100
	v_mov_b32_e32 v0, 0
	s_addc_u32 s38, s11, 0
	s_mov_b32 s3, -2
	v_mov_b32_e32 v1, 0
	v_mov_b64_e32 v[2:3], 0
	v_mov_b64_e32 v[4:5], 0
	v_mov_b64_e32 v[6:7], 0
	v_mov_b64_e32 v[8:9], 0
	v_mov_b64_e32 v[10:11], 0
	v_mov_b64_e32 v[12:13], 0
	v_mov_b64_e32 v[14:15], 0
	v_mov_b64_e32 v[16:17], 0
	v_mov_b64_e32 v[18:19], 0
	v_mov_b64_e32 v[20:21], 0
	v_mov_b64_e32 v[22:23], 0
	v_mov_b64_e32 v[24:25], 0
	v_mov_b64_e32 v[26:27], 0
	v_mov_b64_e32 v[28:29], 0
	v_mov_b64_e32 v[30:31], 0
	v_mov_b64_e32 v[32:33], 0
	v_mov_b64_e32 v[34:35], 0
	v_mov_b64_e32 v[36:37], 0
	v_mov_b64_e32 v[38:39], 0
	v_mov_b64_e32 v[40:41], 0
	v_mov_b64_e32 v[42:43], 0
	v_mov_b64_e32 v[44:45], 0
	v_mov_b64_e32 v[46:47], 0
	v_mov_b64_e32 v[48:49], 0
	v_mov_b64_e32 v[50:51], 0
	v_mov_b64_e32 v[52:53], 0
	v_mov_b64_e32 v[54:55], 0
	v_mov_b64_e32 v[56:57], 0
	v_mov_b64_e32 v[58:59], 0
	v_mov_b64_e32 v[60:61], 0
	v_mov_b64_e32 v[62:63], 0
	v_mov_b64_e32 v[64:65], 0
	v_mov_b64_e32 v[66:67], 0
	v_mov_b64_e32 v[68:69], 0
	v_mov_b64_e32 v[70:71], 0
	v_mov_b64_e32 v[72:73], 0
	v_mov_b64_e32 v[74:75], 0
	v_mov_b64_e32 v[76:77], 0
	v_mov_b64_e32 v[78:79], 0
	v_mov_b64_e32 v[80:81], 0
	v_mov_b64_e32 v[82:83], 0
	v_mov_b64_e32 v[84:85], 0
	v_mov_b64_e32 v[86:87], 0
	v_mov_b64_e32 v[88:89], 0
	v_mov_b64_e32 v[90:91], 0
	v_mov_b64_e32 v[92:93], 0
	v_mov_b64_e32 v[94:95], 0
	v_mov_b64_e32 v[96:97], 0
	v_mov_b64_e32 v[98:99], 0
	v_mov_b64_e32 v[100:101], 0
	v_mov_b64_e32 v[102:103], 0
	v_mov_b64_e32 v[104:105], 0
	v_mov_b64_e32 v[106:107], 0
	v_mov_b64_e32 v[108:109], 0
	v_mov_b64_e32 v[110:111], 0
	v_mov_b64_e32 v[112:113], 0
	v_mov_b64_e32 v[114:115], 0
	v_mov_b64_e32 v[116:117], 0
	v_mov_b64_e32 v[118:119], 0
	v_mov_b64_e32 v[120:121], 0
	v_mov_b64_e32 v[122:123], 0
	v_mov_b64_e32 v[124:125], 0
	v_mov_b64_e32 v[126:127], 0
	ds_read_b128 v[152:155], v149
	ds_read_b128 v[156:159], v149 offset:1024
	ds_read_b128 v[160:163], v149 offset:2048
	ds_read_b128 v[164:167], v149 offset:3072

;     DI const char* a(const Unit& u) const { return (const char*)(A + (size_t)u.pm * BM * lda); }
;     DI const char* a(const Unit& u) const { return (const char*)(A + (size_t)u.pm * BM * 2048 + (u.pn >> 1) * 512); }
;     DI const char* a(const Unit& u) const { return (const char*)((u.pn < 12 ? A1 : A2) + (size_t)u.pm * BM * 512); }
; #define PG8_STAGE(bufoff, gbase, voff) do { _Pragma("unroll") for (int _i = 0; _i < 2; ++_i) \
;         __builtin_amdgcn_global_load_lds((const unsigned*)((const char*)(gbase) + (voff)[_i]), (LAS unsigned*)(lds + (bufoff) + ldsw + _i * 8192), 16, 0, 0); } while (0)
; #define PG8_LDA(dst, b, h) do { _Pragma("unroll") for (int m = 0; m < 4; ++m) _Pragma("unroll") for (int k = 0; k < 2; ++k) dst[m][k] = *(const LAS bf16x8*)(lds + PG8_SA(b, h) + aoff + m * 2048 + k * 1024); } while (0)
; #define PG8_LDB(dst, b, h) do { _Pragma("unroll") for (int n = 0; n < 2; ++n) _Pragma("unroll") for (int k = 0; k < 2; ++k) dst[n][k] = *(const LAS bf16x8*)(lds + PG8_SB(b, h) + boff + n * 2048 + k * 1024); } while (0)
; #define PG8_SCHED __builtin_amdgcn_sched_barrier(0)
; template <class Map, class Epi>
; DI void gemm_phase(LAS unsigned char* lds, const Map& MP, const Epi& E, const int nM, const int nN, const int K, const int lda, const int ldb) {
;     ...
;         const bool has_next = sched_next(ui + 1, nM, nN, G, cblk, nxt);
;         const char* nA = has_next ? MP.a(nxt) : cA; const char* nB = has_next ? MP.b(nxt) : cB;
;         for (int t = 0; t < nt; t += 2) {
;             const bool last = (t == nt - 2);
;             const char* a1 = cA + (size_t)(t + 1) * kstep;
;             const char* a2 = last ? nA : cA + (size_t)(t + 2) * kstep; const char* b2 = last ? nB : cB + (size_t)(t + 2) * kstep;
;             const char* a3 = a2 + kstep; const char* b3 = b2 + kstep;
;             PG8_LDB(B0, 0, 0); PG8_SCHED; PG8_LDA(At, 0, 0); PG8_STAGE(PG8_SA(1, 1), a1 + hstepA, voffA);
;     ...
;         for (int a = 0; a < 2; ++a)
; #pragma unroll
;             for (int b = 0; b < 2; ++b)
; #pragma unroll
;                 for (int m = 0; m < 4; ++m)
; #pragma unroll
;                     for (int n = 0; n < 2; ++n) acc[a][b][m][n] = (f32x4){0.f, 0.f, 0.f, 0.f};
.LBB1_692:
	s_ashr_i32 s15, s14, 31
	v_cmp_lt_i64_e32 vcc, s[16:17], v[140:141]
	s_lshl_b64 s[16:17], s[14:15], 20
	s_add_u32 s16, s5, s16
	s_addc_u32 s17, s26, s17
	s_and_b64 s[18:19], vcc, exec
	s_cselect_b32 s15, s17, s23
	s_cselect_b32 s48, s16, s22
	s_ashr_i32 s13, s12, 31
	s_lshl_b64 s[18:19], s[12:13], 20
	s_add_u32 s18, s27, s18
	s_addc_u32 s19, s28, s19
	s_and_b64 s[24:25], vcc, exec
	s_cselect_b32 s13, s19, s21
	s_cselect_b32 s49, s18, s20
	s_add_u32 s52, s20, 0x100
	s_addc_u32 s53, s21, 0
	s_add_u32 s20, s22, 0x80080
	v_mov_b32_e32 v0, 0
	s_addc_u32 s21, s23, 0
	s_mov_b32 s54, -2
	v_mov_b32_e32 v1, 0
	v_mov_b64_e32 v[2:3], 0
	v_mov_b64_e32 v[4:5], 0
	v_mov_b64_e32 v[6:7], 0
	v_mov_b64_e32 v[8:9], 0
	v_mov_b64_e32 v[10:11], 0
	v_mov_b64_e32 v[12:13], 0
	v_mov_b64_e32 v[14:15], 0
	v_mov_b64_e32 v[16:17], 0
	v_mov_b64_e32 v[18:19], 0
	v_mov_b64_e32 v[20:21], 0
	v_mov_b64_e32 v[22:23], 0
	v_mov_b64_e32 v[24:25], 0
	v_mov_b64_e32 v[26:27], 0
	v_mov_b64_e32 v[28:29], 0
	v_mov_b64_e32 v[30:31], 0
	v_mov_b64_e32 v[32:33], 0
	v_mov_b64_e32 v[34:35], 0
	v_mov_b64_e32 v[36:37], 0
	v_mov_b64_e32 v[38:39], 0
	v_mov_b64_e32 v[40:41], 0
	v_mov_b64_e32 v[42:43], 0
	v_mov_b64_e32 v[44:45], 0
	v_mov_b64_e32 v[46:47], 0
	v_mov_b64_e32 v[48:49], 0
	v_mov_b64_e32 v[50:51], 0
	v_mov_b64_e32 v[52:53], 0
	v_mov_b64_e32 v[54:55], 0
	v_mov_b64_e32 v[56:57], 0
	v_mov_b64_e32 v[58:59], 0
	v_mov_b64_e32 v[60:61], 0
	v_mov_b64_e32 v[62:63], 0
	v_mov_b64_e32 v[64:65], 0
	v_mov_b64_e32 v[66:67], 0
	v_mov_b64_e32 v[68:69], 0
	v_mov_b64_e32 v[70:71], 0
	v_mov_b64_e32 v[72:73], 0
	v_mov_b64_e32 v[74:75], 0
	v_mov_b64_e32 v[76:77], 0
	v_mov_b64_e32 v[78:79], 0
	v_mov_b64_e32 v[80:81], 0
	v_mov_b64_e32 v[82:83], 0
	v_mov_b64_e32 v[84:85], 0
	v_mov_b64_e32 v[86:87], 0
	v_mov_b64_e32 v[88:89], 0
	v_mov_b64_e32 v[90:91], 0
	v_mov_b64_e32 v[92:93], 0
	v_mov_b64_e32 v[94:95], 0
	v_mov_b64_e32 v[96:97], 0
	v_mov_b64_e32 v[98:99], 0
	v_mov_b64_e32 v[100:101], 0
	v_mov_b64_e32 v[102:103], 0
	v_mov_b64_e32 v[104:105], 0
	v_mov_b64_e32 v[106:107], 0
	v_mov_b64_e32 v[108:109], 0
	v_mov_b64_e32 v[110:111], 0
	v_mov_b64_e32 v[112:113], 0
	v_mov_b64_e32 v[114:115], 0
	v_mov_b64_e32 v[116:117], 0
	v_mov_b64_e32 v[118:119], 0
	v_mov_b64_e32 v[120:121], 0
	v_mov_b64_e32 v[122:123], 0
	v_mov_b64_e32 v[124:125], 0
	v_mov_b64_e32 v[126:127], 0
	ds_read_b128 v[150:153], v147
	ds_read_b128 v[154:157], v147 offset:1024
	ds_read_b128 v[158:161], v147 offset:2048
	ds_read_b128 v[162:165], v147 offset:3072

;     DI const char* a(const Unit& u) const { return (const char*)(A + (size_t)u.pm * BM * lda); }
;     DI const char* a(const Unit& u) const { return (const char*)(A + (size_t)u.pm * BM * 2048 + (u.pn >> 1) * 512); }
;     DI const char* a(const Unit& u) const { return (const char*)((u.pn < 12 ? A1 : A2) + (size_t)u.pm * BM * 512); }
; #define PG8_STAGE(bufoff, gbase, voff) do { _Pragma("unroll") for (int _i = 0; _i < 2; ++_i) \
;         __builtin_amdgcn_global_load_lds((const unsigned*)((const char*)(gbase) + (voff)[_i]), (LAS unsigned*)(lds + (bufoff) + ldsw + _i * 8192), 16, 0, 0); } while (0)
; #define PG8_LDA(dst, b, h) do { _Pragma("unroll") for (int m = 0; m < 4; ++m) _Pragma("unroll") for (int k = 0; k < 2; ++k) dst[m][k] = *(const LAS bf16x8*)(lds + PG8_SA(b, h) + aoff + m * 2048 + k * 1024); } while (0)
; #define PG8_LDB(dst, b, h) do { _Pragma("unroll") for (int n = 0; n < 2; ++n) _Pragma("unroll") for (int k = 0; k < 2; ++k) dst[n][k] = *(const LAS bf16x8*)(lds + PG8_SB(b, h) + boff + n * 2048 + k * 1024); } while (0)
; #define PG8_SCHED __builtin_amdgcn_sched_barrier(0)
; template <class Map, class Epi>
; DI void gemm_phase(LAS unsigned char* lds, const Map& MP, const Epi& E, const int nM, const int nN, const int K, const int lda, const int ldb) {
;     ...
;         const bool has_next = sched_next(ui + 1, nM, nN, G, cblk, nxt);
;         const char* nA = has_next ? MP.a(nxt) : cA; const char* nB = has_next ? MP.b(nxt) : cB;
;         for (int t = 0; t < nt; t += 2) {
;             const bool last = (t == nt - 2);
;             const char* a1 = cA + (size_t)(t + 1) * kstep;
;             const char* a2 = last ? nA : cA + (size_t)(t + 2) * kstep; const char* b2 = last ? nB : cB + (size_t)(t + 2) * kstep;
;             const char* a3 = a2 + kstep; const char* b3 = b2 + kstep;
;             PG8_LDB(B0, 0, 0); PG8_SCHED; PG8_LDA(At, 0, 0); PG8_STAGE(PG8_SA(1, 1), a1 + hstepA, voffA);
;     ...
;         for (int a = 0; a < 2; ++a)
; #pragma unroll
;             for (int b = 0; b < 2; ++b)
; #pragma unroll
;                 for (int m = 0; m < 4; ++m)
; #pragma unroll
;                     for (int n = 0; n < 2; ++n) acc[a][b][m][n] = (f32x4){0.f, 0.f, 0.f, 0.f};
.LBB1_924:
	s_ashr_i32 s53, s52, 31
	s_lshl_b64 s[4:5], s[52:53], 20
	s_add_u32 s54, s18, s4
	v_cmp_lt_i64_e32 vcc, s[6:7], v[140:141]
	s_addc_u32 s55, s19, s5
	s_and_b64 s[4:5], vcc, exec
	s_cselect_b32 s4, s55, s13
	s_cselect_b32 s5, s54, s12
	s_ashr_i32 s47, s46, 31
	s_lshl_b64 s[6:7], s[46:47], 20
	s_add_u32 s6, s20, s6
	s_addc_u32 s7, s21, s7
	s_and_b64 s[14:15], vcc, exec
	s_cselect_b32 s37, s7, s11
	s_cselect_b32 s38, s6, s10
	s_add_u32 s39, s10, 0x100
	s_addc_u32 s47, s11, 0
	s_add_u32 s10, s12, 0x80080
	v_mov_b32_e32 v0, 0
	s_addc_u32 s11, s13, 0
	s_mov_b32 s48, -2
	v_mov_b32_e32 v1, 0
	v_mov_b64_e32 v[2:3], 0
	v_mov_b64_e32 v[4:5], 0
	v_mov_b64_e32 v[6:7], 0
	v_mov_b64_e32 v[8:9], 0
	v_mov_b64_e32 v[10:11], 0
	v_mov_b64_e32 v[12:13], 0
	v_mov_b64_e32 v[14:15], 0
	v_mov_b64_e32 v[16:17], 0
	v_mov_b64_e32 v[18:19], 0
	v_mov_b64_e32 v[20:21], 0
	v_mov_b64_e32 v[22:23], 0
	v_mov_b64_e32 v[24:25], 0
	v_mov_b64_e32 v[26:27], 0
	v_mov_b64_e32 v[28:29], 0
	v_mov_b64_e32 v[30:31], 0
	v_mov_b64_e32 v[32:33], 0
	v_mov_b64_e32 v[34:35], 0
	v_mov_b64_e32 v[36:37], 0
	v_mov_b64_e32 v[38:39], 0
	v_mov_b64_e32 v[40:41], 0
	v_mov_b64_e32 v[42:43], 0
	v_mov_b64_e32 v[44:45], 0
	v_mov_b64_e32 v[46:47], 0
	v_mov_b64_e32 v[48:49], 0
	v_mov_b64_e32 v[50:51], 0
	v_mov_b64_e32 v[52:53], 0
	v_mov_b64_e32 v[54:55], 0
	v_mov_b64_e32 v[56:57], 0
	v_mov_b64_e32 v[58:59], 0
	v_mov_b64_e32 v[60:61], 0
	v_mov_b64_e32 v[62:63], 0
	v_mov_b64_e32 v[64:65], 0
	v_mov_b64_e32 v[66:67], 0
	v_mov_b64_e32 v[68:69], 0
	v_mov_b64_e32 v[70:71], 0
	v_mov_b64_e32 v[72:73], 0
	v_mov_b64_e32 v[74:75], 0
	v_mov_b64_e32 v[76:77], 0
	v_mov_b64_e32 v[78:79], 0
	v_mov_b64_e32 v[80:81], 0
	v_mov_b64_e32 v[82:83], 0
	v_mov_b64_e32 v[84:85], 0
	v_mov_b64_e32 v[86:87], 0
	v_mov_b64_e32 v[88:89], 0
	v_mov_b64_e32 v[90:91], 0
	v_mov_b64_e32 v[92:93], 0
	v_mov_b64_e32 v[94:95], 0
	v_mov_b64_e32 v[96:97], 0
	v_mov_b64_e32 v[98:99], 0
	v_mov_b64_e32 v[100:101], 0
	v_mov_b64_e32 v[102:103], 0
	v_mov_b64_e32 v[104:105], 0
	v_mov_b64_e32 v[106:107], 0
	v_mov_b64_e32 v[108:109], 0
	v_mov_b64_e32 v[110:111], 0
	v_mov_b64_e32 v[112:113], 0
	v_mov_b64_e32 v[114:115], 0
	v_mov_b64_e32 v[116:117], 0
	v_mov_b64_e32 v[118:119], 0
	v_mov_b64_e32 v[120:121], 0
	v_mov_b64_e32 v[122:123], 0
	v_mov_b64_e32 v[124:125], 0
	v_mov_b64_e32 v[126:127], 0
	ds_read_b128 v[152:155], v149
	ds_read_b128 v[156:159], v149 offset:1024
	ds_read_b128 v[160:163], v149 offset:2048
	ds_read_b128 v[164:167], v149 offset:3072

;     DI const char* a(const Unit& u) const { return (const char*)(A + (size_t)u.pm * BM * lda); }
;     DI const char* a(const Unit& u) const { return (const char*)(A + (size_t)u.pm * BM * 2048 + (u.pn >> 1) * 512); }
;     DI const char* a(const Unit& u) const { return (const char*)((u.pn < 12 ? A1 : A2) + (size_t)u.pm * BM * 512); }
; #define PG8_STAGE(bufoff, gbase, voff) do { _Pragma("unroll") for (int _i = 0; _i < 2; ++_i) \
;         __builtin_amdgcn_global_load_lds((const unsigned*)((const char*)(gbase) + (voff)[_i]), (LAS unsigned*)(lds + (bufoff) + ldsw + _i * 8192), 16, 0, 0); } while (0)
; #define PG8_LDA(dst, b, h) do { _Pragma("unroll") for (int m = 0; m < 4; ++m) _Pragma("unroll") for (int k = 0; k < 2; ++k) dst[m][k] = *(const LAS bf16x8*)(lds + PG8_SA(b, h) + aoff + m * 2048 + k * 1024); } while (0)
; #define PG8_LDB(dst, b, h) do { _Pragma("unroll") for (int n = 0; n < 2; ++n) _Pragma("unroll") for (int k = 0; k < 2; ++k) dst[n][k] = *(const LAS bf16x8*)(lds + PG8_SB(b, h) + boff + n * 2048 + k * 1024); } while (0)
; #define PG8_SCHED __builtin_amdgcn_sched_barrier(0)
; template <class Map, class Epi>
; DI void gemm_phase(LAS unsigned char* lds, const Map& MP, const Epi& E, const int nM, const int nN, const int K, const int lda, const int ldb) {
;     ...
;         const bool has_next = sched_next(ui + 1, nM, nN, G, cblk, nxt);
;         const char* nA = has_next ? MP.a(nxt) : cA; const char* nB = has_next ? MP.b(nxt) : cB;
;         for (int t = 0; t < nt; t += 2) {
;             const bool last = (t == nt - 2);
;             const char* a1 = cA + (size_t)(t + 1) * kstep;
;             const char* a2 = last ? nA : cA + (size_t)(t + 2) * kstep; const char* b2 = last ? nB : cB + (size_t)(t + 2) * kstep;
;             const char* a3 = a2 + kstep; const char* b3 = b2 + kstep;
;             PG8_LDB(B0, 0, 0); PG8_SCHED; PG8_LDA(At, 0, 0); PG8_STAGE(PG8_SA(1, 1), a1 + hstepA, voffA);
;     ...
;         for (int a = 0; a < 2; ++a)
; #pragma unroll
;             for (int b = 0; b < 2; ++b)
; #pragma unroll
;                 for (int m = 0; m < 4; ++m)
; #pragma unroll
;                     for (int n = 0; n < 2; ++n) acc[a][b][m][n] = (f32x4){0.f, 0.f, 0.f, 0.f};
.LBB1_1068:
	s_ashr_i32 s23, s22, 31
	v_cmp_lt_i64_e32 vcc, s[26:27], v[180:181]
	s_lshl_b64 s[26:27], s[22:23], 20
	s_add_u32 s28, s34, s26
	s_addc_u32 s29, s35, s27
	s_and_b64 s[26:27], vcc, exec
	s_cselect_b32 s23, s29, s25
	s_cselect_b32 s58, s28, s24
	s_ashr_i32 s21, s20, 31
	s_lshl_b64 s[26:27], s[20:21], 20
	s_add_u32 s26, s36, s26
	s_addc_u32 s27, s37, s27
	s_and_b64 s[42:43], vcc, exec
	s_cselect_b32 s21, s27, s47
	s_cselect_b32 s59, s26, s46
	s_add_u32 vcc_lo, s46, 0x100
	s_addc_u32 vcc_hi, s47, 0
	s_add_u32 s42, s24, 0x80080
	v_mov_b32_e32 v0, 0
	s_addc_u32 s43, s25, 0
	s_mov_b32 s3, -2
	v_mov_b32_e32 v1, 0
	v_mov_b64_e32 v[2:3], 0
	v_mov_b64_e32 v[4:5], 0
	v_mov_b64_e32 v[6:7], 0
	v_mov_b64_e32 v[8:9], 0
	v_mov_b64_e32 v[10:11], 0
	v_mov_b64_e32 v[12:13], 0
	v_mov_b64_e32 v[14:15], 0
	v_mov_b64_e32 v[16:17], 0
	v_mov_b64_e32 v[18:19], 0
	v_mov_b64_e32 v[20:21], 0
	v_mov_b64_e32 v[22:23], 0
	v_mov_b64_e32 v[24:25], 0
	v_mov_b64_e32 v[26:27], 0
	v_mov_b64_e32 v[28:29], 0
	v_mov_b64_e32 v[30:31], 0
	v_mov_b64_e32 v[32:33], 0
	v_mov_b64_e32 v[34:35], 0
	v_mov_b64_e32 v[36:37], 0
	v_mov_b64_e32 v[38:39], 0
	v_mov_b64_e32 v[40:41], 0
	v_mov_b64_e32 v[42:43], 0
	v_mov_b64_e32 v[44:45], 0
	v_mov_b64_e32 v[46:47], 0
	v_mov_b64_e32 v[48:49], 0
	v_mov_b64_e32 v[50:51], 0
	v_mov_b64_e32 v[52:53], 0
	v_mov_b64_e32 v[54:55], 0
	v_mov_b64_e32 v[56:57], 0
	v_mov_b64_e32 v[58:59], 0
	v_mov_b64_e32 v[60:61], 0
	v_mov_b64_e32 v[62:63], 0
	v_mov_b64_e32 v[64:65], 0
	v_mov_b64_e32 v[66:67], 0
	v_mov_b64_e32 v[68:69], 0
	v_mov_b64_e32 v[70:71], 0
	v_mov_b64_e32 v[72:73], 0
	v_mov_b64_e32 v[74:75], 0
	v_mov_b64_e32 v[76:77], 0
	v_mov_b64_e32 v[78:79], 0
	v_mov_b64_e32 v[104:105], 0
	v_mov_b64_e32 v[106:107], 0
	v_mov_b64_e32 v[116:117], 0
	v_mov_b64_e32 v[118:119], 0
	v_mov_b64_e32 v[120:121], 0
	v_mov_b64_e32 v[122:123], 0
	v_mov_b64_e32 v[124:125], 0
	v_mov_b64_e32 v[126:127], 0
	v_mov_b64_e32 v[128:129], 0
	v_mov_b64_e32 v[130:131], 0
	v_mov_b64_e32 v[132:133], 0
	v_mov_b64_e32 v[134:135], 0
	v_mov_b64_e32 v[136:137], 0
	v_mov_b64_e32 v[138:139], 0
	v_mov_b64_e32 v[140:141], 0
	v_mov_b64_e32 v[142:143], 0
	v_mov_b64_e32 v[144:145], 0
	v_mov_b64_e32 v[146:147], 0
	v_mov_b64_e32 v[148:149], 0
	v_mov_b64_e32 v[150:151], 0
	v_mov_b64_e32 v[152:153], 0
	v_mov_b64_e32 v[154:155], 0
	v_mov_b64_e32 v[156:157], 0
	v_mov_b64_e32 v[158:159], 0
	ds_read_b128 v[80:83], v189
	ds_read_b128 v[84:87], v189 offset:1024
	ds_read_b128 v[88:91], v189 offset:2048
	ds_read_b128 v[92:95], v189 offset:3072

;     DI const char* a(const Unit& u) const { return (const char*)(A + (size_t)u.pm * BM * lda); }
;     DI const char* a(const Unit& u) const { return (const char*)(A + (size_t)u.pm * BM * 2048 + (u.pn >> 1) * 512); }
;     DI const char* a(const Unit& u) const { return (const char*)((u.pn < 12 ? A1 : A2) + (size_t)u.pm * BM * 512); }
; #define PG8_STAGE(bufoff, gbase, voff) do { _Pragma("unroll") for (int _i = 0; _i < 2; ++_i) \
;         __builtin_amdgcn_global_load_lds((const unsigned*)((const char*)(gbase) + (voff)[_i]), (LAS unsigned*)(lds + (bufoff) + ldsw + _i * 8192), 16, 0, 0); } while (0)
; #define PG8_LDA(dst, b, h) do { _Pragma("unroll") for (int m = 0; m < 4; ++m) _Pragma("unroll") for (int k = 0; k < 2; ++k) dst[m][k] = *(const LAS bf16x8*)(lds + PG8_SA(b, h) + aoff + m * 2048 + k * 1024); } while (0)
; #define PG8_LDB(dst, b, h) do { _Pragma("unroll") for (int n = 0; n < 2; ++n) _Pragma("unroll") for (int k = 0; k < 2; ++k) dst[n][k] = *(const LAS bf16x8*)(lds + PG8_SB(b, h) + boff + n * 2048 + k * 1024); } while (0)
; #define PG8_SCHED __builtin_amdgcn_sched_barrier(0)
; template <class Map, class Epi>
; DI void gemm_phase(LAS unsigned char* lds, const Map& MP, const Epi& E, const int nM, const int nN, const int K, const int lda, const int ldb) {
;     ...
;         const bool has_next = sched_next(ui + 1, nM, nN, G, cblk, nxt);
;         const char* nA = has_next ? MP.a(nxt) : cA; const char* nB = has_next ? MP.b(nxt) : cB;
;         for (int t = 0; t < nt; t += 2) {
;             const bool last = (t == nt - 2);
;             const char* a1 = cA + (size_t)(t + 1) * kstep;
;             const char* a2 = last ? nA : cA + (size_t)(t + 2) * kstep; const char* b2 = last ? nB : cB + (size_t)(t + 2) * kstep;
;             const char* a3 = a2 + kstep; const char* b3 = b2 + kstep;
;             PG8_LDB(B0, 0, 0); PG8_SCHED; PG8_LDA(At, 0, 0); PG8_STAGE(PG8_SA(1, 1), a1 + hstepA, voffA);
;     ...
;         for (int a = 0; a < 2; ++a)
; #pragma unroll
;             for (int b = 0; b < 2; ++b)
; #pragma unroll
;                 for (int m = 0; m < 4; ++m)
; #pragma unroll
;                     for (int n = 0; n < 2; ++n) acc[a][b][m][n] = (f32x4){0.f, 0.f, 0.f, 0.f};
.LBB1_1381:
	s_ashr_i32 s15, s14, 31
	v_cmp_lt_i64_e32 vcc, s[16:17], v[140:141]
	s_lshl_b64 s[16:17], s[14:15], 20
	s_add_u32 s16, s5, s16
	s_addc_u32 s17, s26, s17
	s_and_b64 s[18:19], vcc, exec
	s_cselect_b32 s15, s17, s23
	s_cselect_b32 s48, s16, s22
	s_ashr_i32 s13, s12, 31
	s_lshl_b64 s[18:19], s[12:13], 20
	s_add_u32 s18, s27, s18
	s_addc_u32 s19, s28, s19
	s_and_b64 s[24:25], vcc, exec
	s_cselect_b32 s13, s19, s21
	s_cselect_b32 s49, s18, s20
	s_add_u32 s52, s20, 0x100
	s_addc_u32 s53, s21, 0
	s_add_u32 s20, s22, 0x80080
	v_mov_b32_e32 v0, 0
	s_addc_u32 s21, s23, 0
	s_mov_b32 s3, -2
	v_mov_b32_e32 v1, 0
	v_mov_b64_e32 v[2:3], 0
	v_mov_b64_e32 v[4:5], 0
	v_mov_b64_e32 v[6:7], 0
	v_mov_b64_e32 v[8:9], 0
	v_mov_b64_e32 v[10:11], 0
	v_mov_b64_e32 v[12:13], 0
	v_mov_b64_e32 v[14:15], 0
	v_mov_b64_e32 v[16:17], 0
	v_mov_b64_e32 v[18:19], 0
	v_mov_b64_e32 v[20:21], 0
	v_mov_b64_e32 v[22:23], 0
	v_mov_b64_e32 v[24:25], 0
	v_mov_b64_e32 v[26:27], 0
	v_mov_b64_e32 v[28:29], 0
	v_mov_b64_e32 v[30:31], 0
	v_mov_b64_e32 v[32:33], 0
	v_mov_b64_e32 v[34:35], 0
	v_mov_b64_e32 v[36:37], 0
	v_mov_b64_e32 v[38:39], 0
	v_mov_b64_e32 v[40:41], 0
	v_mov_b64_e32 v[42:43], 0
	v_mov_b64_e32 v[44:45], 0
	v_mov_b64_e32 v[46:47], 0
	v_mov_b64_e32 v[48:49], 0
	v_mov_b64_e32 v[50:51], 0
	v_mov_b64_e32 v[52:53], 0
	v_mov_b64_e32 v[54:55], 0
	v_mov_b64_e32 v[56:57], 0
	v_mov_b64_e32 v[58:59], 0
	v_mov_b64_e32 v[60:61], 0
	v_mov_b64_e32 v[62:63], 0
	v_mov_b64_e32 v[64:65], 0
	v_mov_b64_e32 v[66:67], 0
	v_mov_b64_e32 v[68:69], 0
	v_mov_b64_e32 v[70:71], 0
	v_mov_b64_e32 v[72:73], 0
	v_mov_b64_e32 v[74:75], 0
	v_mov_b64_e32 v[76:77], 0
	v_mov_b64_e32 v[78:79], 0
	v_mov_b64_e32 v[80:81], 0
	v_mov_b64_e32 v[82:83], 0
	v_mov_b64_e32 v[84:85], 0
	v_mov_b64_e32 v[86:87], 0
	v_mov_b64_e32 v[88:89], 0
	v_mov_b64_e32 v[90:91], 0
	v_mov_b64_e32 v[92:93], 0
	v_mov_b64_e32 v[94:95], 0
	v_mov_b64_e32 v[96:97], 0
	v_mov_b64_e32 v[98:99], 0
	v_mov_b64_e32 v[100:101], 0
	v_mov_b64_e32 v[102:103], 0
	v_mov_b64_e32 v[104:105], 0
	v_mov_b64_e32 v[106:107], 0
	v_mov_b64_e32 v[108:109], 0
	v_mov_b64_e32 v[110:111], 0
	v_mov_b64_e32 v[112:113], 0
	v_mov_b64_e32 v[114:115], 0
	v_mov_b64_e32 v[116:117], 0
	v_mov_b64_e32 v[118:119], 0
	v_mov_b64_e32 v[120:121], 0
	v_mov_b64_e32 v[122:123], 0
	v_mov_b64_e32 v[124:125], 0
	v_mov_b64_e32 v[126:127], 0
	ds_read_b128 v[150:153], v147
	ds_read_b128 v[154:157], v147 offset:1024
	ds_read_b128 v[158:161], v147 offset:2048
	ds_read_b128 v[162:165], v147 offset:3072

;     DI const char* a(const Unit& u) const { return (const char*)(A + (size_t)u.pm * BM * lda); }
; #define PG8_STAGE(bufoff, gbase, voff) do { _Pragma("unroll") for (int _i = 0; _i < 2; ++_i) \
;         __builtin_amdgcn_global_load_lds((const unsigned*)((const char*)(gbase) + (voff)[_i]), (LAS unsigned*)(lds + (bufoff) + ldsw + _i * 8192), 16, 0, 0); } while (0)
; #define PG8_LDA(dst, b, h) do { _Pragma("unroll") for (int m = 0; m < 4; ++m) _Pragma("unroll") for (int k = 0; k < 2; ++k) dst[m][k] = *(const LAS bf16x8*)(lds + PG8_SA(b, h) + aoff + m * 2048 + k * 1024); } while (0)
; #define PG8_LDB(dst, b, h) do { _Pragma("unroll") for (int n = 0; n < 2; ++n) _Pragma("unroll") for (int k = 0; k < 2; ++k) dst[n][k] = *(const LAS bf16x8*)(lds + PG8_SB(b, h) + boff + n * 2048 + k * 1024); } while (0)
; #define PG8_SCHED __builtin_amdgcn_sched_barrier(0)
;     DI const char* a(const Unit& u) const { return (const char*)(A + (size_t)u.pm * BM * 2048 + (u.pn >> 1) * 512); }
;     DI const char* a(const Unit& u) const { return (const char*)((u.pn < 12 ? A1 : A2) + (size_t)u.pm * BM * 512); }
; template <class Map, class Epi>
; DI void gemm_phase(LAS unsigned char* lds, const Map& MP, const Epi& E, const int nM, const int nN, const int K, const int lda, const int ldb) {
;     ...
;         const bool has_next = sched_next(ui + 1, nM, nN, G, cblk, nxt);
;         const char* nA = has_next ? MP.a(nxt) : cA; const char* nB = has_next ? MP.b(nxt) : cB;
;         for (int t = 0; t < nt; t += 2) {
;             const bool last = (t == nt - 2);
;             const char* a1 = cA + (size_t)(t + 1) * kstep;
;             const char* a2 = last ? nA : cA + (size_t)(t + 2) * kstep; const char* b2 = last ? nB : cB + (size_t)(t + 2) * kstep;
;             const char* a3 = a2 + kstep; const char* b3 = b2 + kstep;
;             PG8_LDB(B0, 0, 0); PG8_SCHED; PG8_LDA(At, 0, 0); PG8_STAGE(PG8_SA(1, 1), a1 + hstepA, voffA);
;     ...
;         for (int a = 0; a < 2; ++a)
; #pragma unroll
;             for (int b = 0; b < 2; ++b)
; #pragma unroll
;                 for (int m = 0; m < 4; ++m)
; #pragma unroll
;                     for (int n = 0; n < 2; ++n) acc[a][b][m][n] = (f32x4){0.f, 0.f, 0.f, 0.f};
.LBB1_1528:
	s_add_i32 s3, s49, -12
	s_cmp_lt_i32 s49, 12
	s_cselect_b32 s53, s27, s29
	s_cselect_b32 s54, s28, s30
	s_ashr_i32 s13, s49, 31
	s_cmp_lt_i32 s49, 12
	s_cselect_b32 s22, s24, s26
	s_cselect_b32 s23, s5, s25
	s_cselect_b32 s17, s13, 0
	s_cselect_b32 s16, s49, s3
	s_ashr_i32 s13, s12, 31
	v_cmp_lt_i64_e32 vcc, s[14:15], v[140:141]
	s_lshl_b64 s[14:15], s[12:13], 18
	s_add_u32 s14, s23, s14
	s_addc_u32 s15, s22, s15
	s_and_b64 s[22:23], vcc, exec
	s_cselect_b32 s13, s15, s21
	s_cselect_b32 s52, s14, s20
	s_lshl_b64 s[16:17], s[16:17], 18
	s_add_u32 s16, s53, s16
	s_addc_u32 s17, s54, s17
	s_and_b64 s[22:23], vcc, exec
	s_cselect_b32 s53, s17, s19
	s_cselect_b32 s54, s16, s18
	s_add_u32 s55, s18, 0x100
	s_addc_u32 s56, s19, 0
	s_add_u32 s18, s20, 0x20080
	v_mov_b32_e32 v0, 0
	s_addc_u32 s19, s21, 0
	s_mov_b32 s3, -2
	v_mov_b32_e32 v1, 0
	v_mov_b64_e32 v[2:3], 0
	v_mov_b64_e32 v[4:5], 0
	v_mov_b64_e32 v[6:7], 0
	v_mov_b64_e32 v[8:9], 0
	v_mov_b64_e32 v[10:11], 0
	v_mov_b64_e32 v[12:13], 0
	v_mov_b64_e32 v[14:15], 0
	v_mov_b64_e32 v[16:17], 0
	v_mov_b64_e32 v[18:19], 0
	v_mov_b64_e32 v[20:21], 0
	v_mov_b64_e32 v[22:23], 0
	v_mov_b64_e32 v[24:25], 0
	v_mov_b64_e32 v[26:27], 0
	v_mov_b64_e32 v[28:29], 0
	v_mov_b64_e32 v[30:31], 0
	v_mov_b64_e32 v[32:33], 0
	v_mov_b64_e32 v[34:35], 0
	v_mov_b64_e32 v[36:37], 0
	v_mov_b64_e32 v[38:39], 0
	v_mov_b64_e32 v[40:41], 0
	v_mov_b64_e32 v[42:43], 0
	v_mov_b64_e32 v[44:45], 0
	v_mov_b64_e32 v[46:47], 0
	v_mov_b64_e32 v[48:49], 0
	v_mov_b64_e32 v[50:51], 0
	v_mov_b64_e32 v[52:53], 0
	v_mov_b64_e32 v[54:55], 0
	v_mov_b64_e32 v[56:57], 0
	v_mov_b64_e32 v[58:59], 0
	v_mov_b64_e32 v[60:61], 0
	v_mov_b64_e32 v[62:63], 0
	v_mov_b64_e32 v[64:65], 0
	v_mov_b64_e32 v[66:67], 0
	v_mov_b64_e32 v[68:69], 0
	v_mov_b64_e32 v[70:71], 0
	v_mov_b64_e32 v[72:73], 0
	v_mov_b64_e32 v[74:75], 0
	v_mov_b64_e32 v[76:77], 0
	v_mov_b64_e32 v[78:79], 0
	v_mov_b64_e32 v[80:81], 0
	v_mov_b64_e32 v[82:83], 0
	v_mov_b64_e32 v[84:85], 0
	v_mov_b64_e32 v[86:87], 0
	v_mov_b64_e32 v[88:89], 0
	v_mov_b64_e32 v[90:91], 0
	v_mov_b64_e32 v[92:93], 0
	v_mov_b64_e32 v[94:95], 0
	v_mov_b64_e32 v[96:97], 0
	v_mov_b64_e32 v[98:99], 0
	v_mov_b64_e32 v[100:101], 0
	v_mov_b64_e32 v[102:103], 0
	v_mov_b64_e32 v[104:105], 0
	v_mov_b64_e32 v[106:107], 0
	v_mov_b64_e32 v[108:109], 0
	v_mov_b64_e32 v[110:111], 0
	v_mov_b64_e32 v[112:113], 0
	v_mov_b64_e32 v[114:115], 0
	v_mov_b64_e32 v[116:117], 0
	v_mov_b64_e32 v[118:119], 0
	v_mov_b64_e32 v[120:121], 0
	v_mov_b64_e32 v[122:123], 0
	v_mov_b64_e32 v[124:125], 0
	v_mov_b64_e32 v[126:127], 0
	ds_read_b128 v[150:153], v147
	ds_read_b128 v[154:157], v147 offset:1024
	ds_read_b128 v[158:161], v147 offset:2048
	ds_read_b128 v[162:165], v147 offset:3072

;     DI const char* a(const Unit& u) const { return (const char*)(A + (size_t)u.pm * BM * lda); }
;     DI const char* a(const Unit& u) const { return (const char*)(A + (size_t)u.pm * BM * 2048 + (u.pn >> 1) * 512); }
;     DI const char* a(const Unit& u) const { return (const char*)((u.pn < 12 ? A1 : A2) + (size_t)u.pm * BM * 512); }
; #define PG8_STAGE(bufoff, gbase, voff) do { _Pragma("unroll") for (int _i = 0; _i < 2; ++_i) \
;         __builtin_amdgcn_global_load_lds((const unsigned*)((const char*)(gbase) + (voff)[_i]), (LAS unsigned*)(lds + (bufoff) + ldsw + _i * 8192), 16, 0, 0); } while (0)
; #define PG8_LDA(dst, b, h) do { _Pragma("unroll") for (int m = 0; m < 4; ++m) _Pragma("unroll") for (int k = 0; k < 2; ++k) dst[m][k] = *(const LAS bf16x8*)(lds + PG8_SA(b, h) + aoff + m * 2048 + k * 1024); } while (0)
; #define PG8_LDB(dst, b, h) do { _Pragma("unroll") for (int n = 0; n < 2; ++n) _Pragma("unroll") for (int k = 0; k < 2; ++k) dst[n][k] = *(const LAS bf16x8*)(lds + PG8_SB(b, h) + boff + n * 2048 + k * 1024); } while (0)
; #define PG8_SCHED __builtin_amdgcn_sched_barrier(0)
; template <class Map, class Epi>
; DI void gemm_phase(LAS unsigned char* lds, const Map& MP, const Epi& E, const int nM, const int nN, const int K, const int lda, const int ldb) {
;     ...
;         const bool has_next = sched_next(ui + 1, nM, nN, G, cblk, nxt);
;         const char* nA = has_next ? MP.a(nxt) : cA; const char* nB = has_next ? MP.b(nxt) : cB;
;         for (int t = 0; t < nt; t += 2) {
;             const bool last = (t == nt - 2);
;             const char* a1 = cA + (size_t)(t + 1) * kstep;
;             const char* a2 = last ? nA : cA + (size_t)(t + 2) * kstep; const char* b2 = last ? nB : cB + (size_t)(t + 2) * kstep;
;             const char* a3 = a2 + kstep; const char* b3 = b2 + kstep;
;             PG8_LDB(B0, 0, 0); PG8_SCHED; PG8_LDA(At, 0, 0); PG8_STAGE(PG8_SA(1, 1), a1 + hstepA, voffA);
;     ...
;         for (int a = 0; a < 2; ++a)
; #pragma unroll
;             for (int b = 0; b < 2; ++b)
; #pragma unroll
;                 for (int m = 0; m < 4; ++m)
; #pragma unroll
;                     for (int n = 0; n < 2; ++n) acc[a][b][m][n] = (f32x4){0.f, 0.f, 0.f, 0.f};
.LBB1_1763:
	s_ashr_i32 s47, s46, 31
	v_cmp_lt_i64_e32 vcc, s[6:7], v[140:141]
	s_lshl_b64 s[6:7], s[46:47], 20
	s_add_u32 s52, s18, s6
	s_addc_u32 s53, s19, s7
	s_and_b64 s[6:7], vcc, exec
	s_cselect_b32 s37, s53, s13
	s_cselect_b32 s38, s52, s12
	s_ashr_i32 s45, s44, 31
	s_lshl_b64 s[6:7], s[44:45], 20
	s_add_u32 s6, s20, s6
	s_addc_u32 s7, s21, s7
	s_and_b64 s[14:15], vcc, exec
	s_cselect_b32 s39, s7, s11
	s_cselect_b32 s45, s6, s10
	s_add_u32 s47, s10, 0x100
	s_addc_u32 s48, s11, 0
	s_add_u32 s10, s12, 0x80080
	v_mov_b32_e32 v0, 0
	s_addc_u32 s11, s13, 0
	s_mov_b32 s3, -2
	v_mov_b32_e32 v1, 0
	v_mov_b64_e32 v[2:3], 0
	v_mov_b64_e32 v[4:5], 0
	v_mov_b64_e32 v[6:7], 0
	v_mov_b64_e32 v[8:9], 0
	v_mov_b64_e32 v[10:11], 0
	v_mov_b64_e32 v[12:13], 0
	v_mov_b64_e32 v[14:15], 0
	v_mov_b64_e32 v[16:17], 0
	v_mov_b64_e32 v[18:19], 0
	v_mov_b64_e32 v[20:21], 0
	v_mov_b64_e32 v[22:23], 0
	v_mov_b64_e32 v[24:25], 0
	v_mov_b64_e32 v[26:27], 0
	v_mov_b64_e32 v[28:29], 0
	v_mov_b64_e32 v[30:31], 0
	v_mov_b64_e32 v[32:33], 0
	v_mov_b64_e32 v[34:35], 0
	v_mov_b64_e32 v[36:37], 0
	v_mov_b64_e32 v[38:39], 0
	v_mov_b64_e32 v[40:41], 0
	v_mov_b64_e32 v[42:43], 0
	v_mov_b64_e32 v[44:45], 0
	v_mov_b64_e32 v[46:47], 0
	v_mov_b64_e32 v[48:49], 0
	v_mov_b64_e32 v[50:51], 0
	v_mov_b64_e32 v[52:53], 0
	v_mov_b64_e32 v[54:55], 0
	v_mov_b64_e32 v[56:57], 0
	v_mov_b64_e32 v[58:59], 0
	v_mov_b64_e32 v[60:61], 0
	v_mov_b64_e32 v[62:63], 0
	v_mov_b64_e32 v[64:65], 0
	v_mov_b64_e32 v[66:67], 0
	v_mov_b64_e32 v[68:69], 0
	v_mov_b64_e32 v[70:71], 0
	v_mov_b64_e32 v[72:73], 0
	v_mov_b64_e32 v[74:75], 0
	v_mov_b64_e32 v[76:77], 0
	v_mov_b64_e32 v[78:79], 0
	v_mov_b64_e32 v[80:81], 0
	v_mov_b64_e32 v[82:83], 0
	v_mov_b64_e32 v[84:85], 0
	v_mov_b64_e32 v[86:87], 0
	v_mov_b64_e32 v[88:89], 0
	v_mov_b64_e32 v[90:91], 0
	v_mov_b64_e32 v[92:93], 0
	v_mov_b64_e32 v[94:95], 0
	v_mov_b64_e32 v[96:97], 0
	v_mov_b64_e32 v[98:99], 0
	v_mov_b64_e32 v[100:101], 0
	v_mov_b64_e32 v[102:103], 0
	v_mov_b64_e32 v[104:105], 0
	v_mov_b64_e32 v[106:107], 0
	v_mov_b64_e32 v[108:109], 0
	v_mov_b64_e32 v[110:111], 0
	v_mov_b64_e32 v[112:113], 0
	v_mov_b64_e32 v[114:115], 0
	v_mov_b64_e32 v[116:117], 0
	v_mov_b64_e32 v[118:119], 0
	v_mov_b64_e32 v[120:121], 0
	v_mov_b64_e32 v[122:123], 0
	v_mov_b64_e32 v[124:125], 0
	v_mov_b64_e32 v[126:127], 0
	ds_read_b128 v[152:155], v149
	ds_read_b128 v[156:159], v149 offset:1024
	ds_read_b128 v[160:163], v149 offset:2048
	ds_read_b128 v[164:167], v149 offset:3072

;     DI const char* a(const Unit& u) const { return (const char*)(A + (size_t)u.pm * BM * lda); }
;     DI const char* a(const Unit& u) const { return (const char*)(A + (size_t)u.pm * BM * 2048 + (u.pn >> 1) * 512); }
;     DI const char* a(const Unit& u) const { return (const char*)((u.pn < 12 ? A1 : A2) + (size_t)u.pm * BM * 512); }
; #define PG8_STAGE(bufoff, gbase, voff) do { _Pragma("unroll") for (int _i = 0; _i < 2; ++_i) \
;         __builtin_amdgcn_global_load_lds((const unsigned*)((const char*)(gbase) + (voff)[_i]), (LAS unsigned*)(lds + (bufoff) + ldsw + _i * 8192), 16, 0, 0); } while (0)
; #define PG8_LDA(dst, b, h) do { _Pragma("unroll") for (int m = 0; m < 4; ++m) _Pragma("unroll") for (int k = 0; k < 2; ++k) dst[m][k] = *(const LAS bf16x8*)(lds + PG8_SA(b, h) + aoff + m * 2048 + k * 1024); } while (0)
; #define PG8_LDB(dst, b, h) do { _Pragma("unroll") for (int n = 0; n < 2; ++n) _Pragma("unroll") for (int k = 0; k < 2; ++k) dst[n][k] = *(const LAS bf16x8*)(lds + PG8_SB(b, h) + boff + n * 2048 + k * 1024); } while (0)
; #define PG8_SCHED __builtin_amdgcn_sched_barrier(0)
; template <class Map, class Epi>
; DI void gemm_phase(LAS unsigned char* lds, const Map& MP, const Epi& E, const int nM, const int nN, const int K, const int lda, const int ldb) {
;     ...
;         const bool has_next = sched_next(ui + 1, nM, nN, G, cblk, nxt);
;         const char* nA = has_next ? MP.a(nxt) : cA; const char* nB = has_next ? MP.b(nxt) : cB;
;         for (int t = 0; t < nt; t += 2) {
;             const bool last = (t == nt - 2);
;             const char* a1 = cA + (size_t)(t + 1) * kstep;
;             const char* a2 = last ? nA : cA + (size_t)(t + 2) * kstep; const char* b2 = last ? nB : cB + (size_t)(t + 2) * kstep;
;             const char* a3 = a2 + kstep; const char* b3 = b2 + kstep;
;             PG8_LDB(B0, 0, 0); PG8_SCHED; PG8_LDA(At, 0, 0); PG8_STAGE(PG8_SA(1, 1), a1 + hstepA, voffA);
;     ...
;         for (int a = 0; a < 2; ++a)
; #pragma unroll
;             for (int b = 0; b < 2; ++b)
; #pragma unroll
;                 for (int m = 0; m < 4; ++m)
; #pragma unroll
;                     for (int n = 0; n < 2; ++n) acc[a][b][m][n] = (f32x4){0.f, 0.f, 0.f, 0.f};
.LBB1_1907:
	s_ashr_i32 s23, s22, 31
	v_cmp_lt_i64_e32 vcc, s[24:25], v[180:181]
	s_lshl_b64 s[24:25], s[22:23], 20
	s_add_u32 s24, s34, s24
	s_addc_u32 s25, s35, s25
	s_and_b64 s[26:27], vcc, exec
	s_cselect_b32 s23, s25, s29
	s_cselect_b32 s58, s24, s28
	s_ashr_i32 s21, s20, 31
	s_lshl_b64 s[26:27], s[20:21], 20
	s_add_u32 s26, s36, s26
	s_addc_u32 s27, s37, s27
	s_and_b64 s[42:43], vcc, exec
	s_cselect_b32 s21, s27, s47
	s_cselect_b32 s59, s26, s46
	s_add_u32 vcc_lo, s46, 0x100
	s_addc_u32 vcc_hi, s47, 0
	s_add_u32 s42, s28, 0x80080
	v_mov_b32_e32 v0, 0
	s_addc_u32 s43, s29, 0
	s_mov_b32 s3, -2
	v_mov_b32_e32 v1, 0
	v_mov_b64_e32 v[2:3], 0
	v_mov_b64_e32 v[4:5], 0
	v_mov_b64_e32 v[6:7], 0
	v_mov_b64_e32 v[8:9], 0
	v_mov_b64_e32 v[10:11], 0
	v_mov_b64_e32 v[12:13], 0
	v_mov_b64_e32 v[14:15], 0
	v_mov_b64_e32 v[16:17], 0
	v_mov_b64_e32 v[18:19], 0
	v_mov_b64_e32 v[20:21], 0
	v_mov_b64_e32 v[22:23], 0
	v_mov_b64_e32 v[24:25], 0
	v_mov_b64_e32 v[26:27], 0
	v_mov_b64_e32 v[28:29], 0
	v_mov_b64_e32 v[30:31], 0
	v_mov_b64_e32 v[32:33], 0
	v_mov_b64_e32 v[34:35], 0
	v_mov_b64_e32 v[36:37], 0
	v_mov_b64_e32 v[38:39], 0
	v_mov_b64_e32 v[40:41], 0
	v_mov_b64_e32 v[42:43], 0
	v_mov_b64_e32 v[44:45], 0
	v_mov_b64_e32 v[46:47], 0
	v_mov_b64_e32 v[48:49], 0
	v_mov_b64_e32 v[50:51], 0
	v_mov_b64_e32 v[52:53], 0
	v_mov_b64_e32 v[54:55], 0
	v_mov_b64_e32 v[56:57], 0
	v_mov_b64_e32 v[58:59], 0
	v_mov_b64_e32 v[60:61], 0
	v_mov_b64_e32 v[62:63], 0
	v_mov_b64_e32 v[64:65], 0
	v_mov_b64_e32 v[66:67], 0
	v_mov_b64_e32 v[68:69], 0
	v_mov_b64_e32 v[70:71], 0
	v_mov_b64_e32 v[72:73], 0
	v_mov_b64_e32 v[74:75], 0
	v_mov_b64_e32 v[76:77], 0
	v_mov_b64_e32 v[78:79], 0
	v_mov_b64_e32 v[104:105], 0
	v_mov_b64_e32 v[106:107], 0
	v_mov_b64_e32 v[116:117], 0
	v_mov_b64_e32 v[118:119], 0
	v_mov_b64_e32 v[120:121], 0
	v_mov_b64_e32 v[122:123], 0
	v_mov_b64_e32 v[124:125], 0
	v_mov_b64_e32 v[126:127], 0
	v_mov_b64_e32 v[128:129], 0
	v_mov_b64_e32 v[130:131], 0
	v_mov_b64_e32 v[132:133], 0
	v_mov_b64_e32 v[134:135], 0
	v_mov_b64_e32 v[136:137], 0
	v_mov_b64_e32 v[138:139], 0
	v_mov_b64_e32 v[140:141], 0
	v_mov_b64_e32 v[142:143], 0
	v_mov_b64_e32 v[144:145], 0
	v_mov_b64_e32 v[146:147], 0
	v_mov_b64_e32 v[148:149], 0
	v_mov_b64_e32 v[150:151], 0
	v_mov_b64_e32 v[152:153], 0
	v_mov_b64_e32 v[154:155], 0
	v_mov_b64_e32 v[156:157], 0
	v_mov_b64_e32 v[158:159], 0
	ds_read_b128 v[80:83], v189
	ds_read_b128 v[84:87], v189 offset:1024
	ds_read_b128 v[88:91], v189 offset:2048
	ds_read_b128 v[92:95], v189 offset:3072

;     DI const char* a(const Unit& u) const { return (const char*)(A + (size_t)u.pm * BM * lda); }
;     DI const char* a(const Unit& u) const { return (const char*)(A + (size_t)u.pm * BM * 2048 + (u.pn >> 1) * 512); }
;     DI const char* a(const Unit& u) const { return (const char*)((u.pn < 12 ? A1 : A2) + (size_t)u.pm * BM * 512); }
; #define PG8_STAGE(bufoff, gbase, voff) do { _Pragma("unroll") for (int _i = 0; _i < 2; ++_i) \
;         __builtin_amdgcn_global_load_lds((const unsigned*)((const char*)(gbase) + (voff)[_i]), (LAS unsigned*)(lds + (bufoff) + ldsw + _i * 8192), 16, 0, 0); } while (0)
; #define PG8_LDA(dst, b, h) do { _Pragma("unroll") for (int m = 0; m < 4; ++m) _Pragma("unroll") for (int k = 0; k < 2; ++k) dst[m][k] = *(const LAS bf16x8*)(lds + PG8_SA(b, h) + aoff + m * 2048 + k * 1024); } while (0)
; #define PG8_LDB(dst, b, h) do { _Pragma("unroll") for (int n = 0; n < 2; ++n) _Pragma("unroll") for (int k = 0; k < 2; ++k) dst[n][k] = *(const LAS bf16x8*)(lds + PG8_SB(b, h) + boff + n * 2048 + k * 1024); } while (0)
; #define PG8_SCHED __builtin_amdgcn_sched_barrier(0)
; template <class Map, class Epi>
; DI void gemm_phase(LAS unsigned char* lds, const Map& MP, const Epi& E, const int nM, const int nN, const int K, const int lda, const int ldb) {
;     ...
;             const char* a1 = cA + (size_t)(t + 1) * kstep;
;             const char* a2 = last ? nA : cA + (size_t)(t + 2) * kstep; const char* b2 = last ? nB : cB + (size_t)(t + 2) * kstep;
;             const char* a3 = a2 + kstep; const char* b3 = b2 + kstep;
;             PG8_LDB(B0, 0, 0); PG8_SCHED; PG8_LDA(At, 0, 0); PG8_STAGE(PG8_SA(1, 1), a1 + hstepA, voffA);
;     ...
;         for (int a = 0; a < 2; ++a)
; #pragma unroll
;             for (int b = 0; b < 2; ++b)
; #pragma unroll
;                 for (int m = 0; m < 4; ++m)
; #pragma unroll
;                     for (int n = 0; n < 2; ++n) acc[a][b][m][n] = (f32x4){0.f, 0.f, 0.f, 0.f};
.LBB1_2077:
	s_add_u32 s39, s10, 0x100
	v_mov_b32_e32 v0, 0
	s_addc_u32 s44, s11, 0
	s_mov_b32 s3, -2
	v_mov_b32_e32 v1, 0
	v_mov_b64_e32 v[2:3], 0
	v_mov_b64_e32 v[4:5], 0
	v_mov_b64_e32 v[6:7], 0
	v_mov_b64_e32 v[8:9], 0
	v_mov_b64_e32 v[10:11], 0
	v_mov_b64_e32 v[12:13], 0
	v_mov_b64_e32 v[14:15], 0
	v_mov_b64_e32 v[16:17], 0
	v_mov_b64_e32 v[18:19], 0
	v_mov_b64_e32 v[20:21], 0
	v_mov_b64_e32 v[22:23], 0
	v_mov_b64_e32 v[24:25], 0
	v_mov_b64_e32 v[26:27], 0
	v_mov_b64_e32 v[28:29], 0
	v_mov_b64_e32 v[30:31], 0
	v_mov_b64_e32 v[32:33], 0
	v_mov_b64_e32 v[34:35], 0
	v_mov_b64_e32 v[36:37], 0
	v_mov_b64_e32 v[38:39], 0
	v_mov_b64_e32 v[40:41], 0
	v_mov_b64_e32 v[42:43], 0
	v_mov_b64_e32 v[44:45], 0
	v_mov_b64_e32 v[46:47], 0
	v_mov_b64_e32 v[48:49], 0
	v_mov_b64_e32 v[50:51], 0
	v_mov_b64_e32 v[52:53], 0
	v_mov_b64_e32 v[54:55], 0
	v_mov_b64_e32 v[56:57], 0
	v_mov_b64_e32 v[58:59], 0
	v_mov_b64_e32 v[60:61], 0
	v_mov_b64_e32 v[62:63], 0
	v_mov_b64_e32 v[64:65], 0
	v_mov_b64_e32 v[66:67], 0
	v_mov_b64_e32 v[68:69], 0
	v_mov_b64_e32 v[70:71], 0
	v_mov_b64_e32 v[72:73], 0
	v_mov_b64_e32 v[74:75], 0
	v_mov_b64_e32 v[76:77], 0
	v_mov_b64_e32 v[78:79], 0
	v_mov_b64_e32 v[80:81], 0
	v_mov_b64_e32 v[82:83], 0
	v_mov_b64_e32 v[84:85], 0
	v_mov_b64_e32 v[86:87], 0
	v_mov_b64_e32 v[88:89], 0
	v_mov_b64_e32 v[90:91], 0
	v_mov_b64_e32 v[92:93], 0
	v_mov_b64_e32 v[94:95], 0
	v_mov_b64_e32 v[96:97], 0
	v_mov_b64_e32 v[98:99], 0
	v_mov_b64_e32 v[100:101], 0
	v_mov_b64_e32 v[102:103], 0
	v_mov_b64_e32 v[104:105], 0
	v_mov_b64_e32 v[106:107], 0
	v_mov_b64_e32 v[108:109], 0
	v_mov_b64_e32 v[110:111], 0
	v_mov_b64_e32 v[112:113], 0
	v_mov_b64_e32 v[114:115], 0
	v_mov_b64_e32 v[116:117], 0
	v_mov_b64_e32 v[118:119], 0
	v_mov_b64_e32 v[120:121], 0
	v_mov_b64_e32 v[122:123], 0
	v_mov_b64_e32 v[124:125], 0
	v_mov_b64_e32 v[126:127], 0
	ds_read_b128 v[152:155], v149
	ds_read_b128 v[156:159], v149 offset:1024
	ds_read_b128 v[160:163], v149 offset:2048
	ds_read_b128 v[164:167], v149 offset:3072

;     DI const char* a(const Unit& u) const { return (const char*)(A + (size_t)u.pm * BM * lda); }
;     DI const char* a(const Unit& u) const { return (const char*)((u.pn < 12 ? A1 : A2) + (size_t)u.pm * BM * 512); }
; #define PG8_STAGE(bufoff, gbase, voff) do { _Pragma("unroll") for (int _i = 0; _i < 2; ++_i) \
;         __builtin_amdgcn_global_load_lds((const unsigned*)((const char*)(gbase) + (voff)[_i]), (LAS unsigned*)(lds + (bufoff) + ldsw + _i * 8192), 16, 0, 0); } while (0)
; #define PG8_LDA(dst, b, h) do { _Pragma("unroll") for (int m = 0; m < 4; ++m) _Pragma("unroll") for (int k = 0; k < 2; ++k) dst[m][k] = *(const LAS bf16x8*)(lds + PG8_SA(b, h) + aoff + m * 2048 + k * 1024); } while (0)
; #define PG8_LDB(dst, b, h) do { _Pragma("unroll") for (int n = 0; n < 2; ++n) _Pragma("unroll") for (int k = 0; k < 2; ++k) dst[n][k] = *(const LAS bf16x8*)(lds + PG8_SB(b, h) + boff + n * 2048 + k * 1024); } while (0)
; #define PG8_SCHED __builtin_amdgcn_sched_barrier(0)
;     DI const char* a(const Unit& u) const { return (const char*)(A + (size_t)u.pm * BM * 2048 + (u.pn >> 1) * 512); }
; template <class Map, class Epi>
; DI void gemm_phase(LAS unsigned char* lds, const Map& MP, const Epi& E, const int nM, const int nN, const int K, const int lda, const int ldb) {
;     ...
;         const bool has_next = sched_next(ui + 1, nM, nN, G, cblk, nxt);
;         const char* nA = has_next ? MP.a(nxt) : cA; const char* nB = has_next ? MP.b(nxt) : cB;
;         for (int t = 0; t < nt; t += 2) {
;             const bool last = (t == nt - 2);
;             const char* a1 = cA + (size_t)(t + 1) * kstep;
;             const char* a2 = last ? nA : cA + (size_t)(t + 2) * kstep; const char* b2 = last ? nB : cB + (size_t)(t + 2) * kstep;
;             const char* a3 = a2 + kstep; const char* b3 = b2 + kstep;
;             PG8_LDB(B0, 0, 0); PG8_SCHED; PG8_LDA(At, 0, 0); PG8_STAGE(PG8_SA(1, 1), a1 + hstepA, voffA);
;     ...
;         for (int a = 0; a < 2; ++a)
; #pragma unroll
;             for (int b = 0; b < 2; ++b)
; #pragma unroll
;                 for (int m = 0; m < 4; ++m)
; #pragma unroll
;                     for (int n = 0; n < 2; ++n) acc[a][b][m][n] = (f32x4){0.f, 0.f, 0.f, 0.f};
.LBB1_2338:
	s_ashr_i32 s53, s52, 31
	v_cmp_lt_i64_e32 vcc, s[6:7], v[156:157]
	s_lshl_b64 s[6:7], s[52:53], 20
	s_add_u32 s3, s18, s6
	s_addc_u32 s14, s19, s7
	s_lshl_b32 s6, s37, 8
	s_and_b32 s6, s6, 0xfffffe00
	s_ashr_i32 s7, s6, 31
	s_lshl_b64 s[6:7], s[6:7], 1
	s_add_u32 s6, s3, s6
	s_addc_u32 s7, s14, s7
	s_and_b64 s[14:15], vcc, exec
	s_cselect_b32 s38, s7, s13
	s_cselect_b32 s39, s6, s12
	s_ashr_i32 s14, s37, 1
	s_ashr_i32 s15, s14, 31
	s_lshl_b64 s[14:15], s[14:15], 19
	s_add_u32 s3, s20, s14
	s_addc_u32 s14, s21, s15
	s_lshl_b32 s15, s37, 18
	s_and_b32 s15, s15, 0x40000
	s_add_u32 s54, s3, s15
	s_addc_u32 s55, s14, 0
	s_and_b64 s[14:15], vcc, exec
	s_cselect_b32 s48, s55, s11
	s_cselect_b32 s49, s54, s10
	s_add_u32 s53, s10, 0x100
	s_addc_u32 s56, s11, 0
	s_add_u32 s10, s12, 0x80080
	v_mov_b32_e32 v0, 0
	s_addc_u32 s11, s13, 0
	s_mov_b32 s3, -2
	v_mov_b32_e32 v1, 0
	v_mov_b64_e32 v[2:3], 0
	v_mov_b64_e32 v[4:5], 0
	v_mov_b64_e32 v[6:7], 0
	v_mov_b64_e32 v[8:9], 0
	v_mov_b64_e32 v[10:11], 0
	v_mov_b64_e32 v[12:13], 0
	v_mov_b64_e32 v[14:15], 0
	v_mov_b64_e32 v[16:17], 0
	v_mov_b64_e32 v[18:19], 0
	v_mov_b64_e32 v[20:21], 0
	v_mov_b64_e32 v[22:23], 0
	v_mov_b64_e32 v[24:25], 0
	v_mov_b64_e32 v[26:27], 0
	v_mov_b64_e32 v[28:29], 0
	v_mov_b64_e32 v[30:31], 0
	v_mov_b64_e32 v[32:33], 0
	v_mov_b64_e32 v[34:35], 0
	v_mov_b64_e32 v[36:37], 0
	v_mov_b64_e32 v[38:39], 0
	v_mov_b64_e32 v[48:49], 0
	v_mov_b64_e32 v[50:51], 0
	v_mov_b64_e32 v[52:53], 0
	v_mov_b64_e32 v[54:55], 0
	v_mov_b64_e32 v[64:65], 0
	v_mov_b64_e32 v[66:67], 0
	v_mov_b64_e32 v[68:69], 0
	v_mov_b64_e32 v[70:71], 0
	v_mov_b64_e32 v[72:73], 0
	v_mov_b64_e32 v[74:75], 0
	v_mov_b64_e32 v[76:77], 0
	v_mov_b64_e32 v[78:79], 0
	v_mov_b64_e32 v[80:81], 0
	v_mov_b64_e32 v[82:83], 0
	v_mov_b64_e32 v[84:85], 0
	v_mov_b64_e32 v[86:87], 0
	v_mov_b64_e32 v[88:89], 0
	v_mov_b64_e32 v[90:91], 0
	v_mov_b64_e32 v[92:93], 0
	v_mov_b64_e32 v[94:95], 0
	v_mov_b64_e32 v[96:97], 0
	v_mov_b64_e32 v[98:99], 0
	v_mov_b64_e32 v[100:101], 0
	v_mov_b64_e32 v[102:103], 0
	v_mov_b64_e32 v[104:105], 0
	v_mov_b64_e32 v[106:107], 0
	v_mov_b64_e32 v[108:109], 0
	v_mov_b64_e32 v[110:111], 0
	v_mov_b64_e32 v[112:113], 0
	v_mov_b64_e32 v[114:115], 0
	v_mov_b64_e32 v[116:117], 0
	v_mov_b64_e32 v[118:119], 0
	v_mov_b64_e32 v[120:121], 0
	v_mov_b64_e32 v[122:123], 0
	v_mov_b64_e32 v[124:125], 0
	v_mov_b64_e32 v[126:127], 0
	v_mov_b64_e32 v[128:129], 0
	v_mov_b64_e32 v[130:131], 0
	v_mov_b64_e32 v[132:133], 0
	v_mov_b64_e32 v[134:135], 0
	v_mov_b64_e32 v[136:137], 0
	v_mov_b64_e32 v[138:139], 0
	v_mov_b64_e32 v[140:141], 0
	v_mov_b64_e32 v[142:143], 0
	ds_read_b128 v[40:43], v165
	ds_read_b128 v[44:47], v165 offset:1024
	ds_read_b128 v[56:59], v165 offset:2048
	ds_read_b128 v[60:63], v165 offset:3072

;     DI const char* a(const Unit& u) const { return (const char*)(A + (size_t)u.pm * BM * lda); }
;     DI const char* a(const Unit& u) const { return (const char*)(A + (size_t)u.pm * BM * 2048 + (u.pn >> 1) * 512); }
;     DI const char* a(const Unit& u) const { return (const char*)((u.pn < 12 ? A1 : A2) + (size_t)u.pm * BM * 512); }
; #define PG8_STAGE(bufoff, gbase, voff) do { _Pragma("unroll") for (int _i = 0; _i < 2; ++_i) \
;         __builtin_amdgcn_global_load_lds((const unsigned*)((const char*)(gbase) + (voff)[_i]), (LAS unsigned*)(lds + (bufoff) + ldsw + _i * 8192), 16, 0, 0); } while (0)
; #define PG8_LDA(dst, b, h) do { _Pragma("unroll") for (int m = 0; m < 4; ++m) _Pragma("unroll") for (int k = 0; k < 2; ++k) dst[m][k] = *(const LAS bf16x8*)(lds + PG8_SA(b, h) + aoff + m * 2048 + k * 1024); } while (0)
; #define PG8_LDB(dst, b, h) do { _Pragma("unroll") for (int n = 0; n < 2; ++n) _Pragma("unroll") for (int k = 0; k < 2; ++k) dst[n][k] = *(const LAS bf16x8*)(lds + PG8_SB(b, h) + boff + n * 2048 + k * 1024); } while (0)
; #define PG8_SCHED __builtin_amdgcn_sched_barrier(0)
; template <class Map, class Epi>
; DI void gemm_phase(LAS unsigned char* lds, const Map& MP, const Epi& E, const int nM, const int nN, const int K, const int lda, const int ldb) {
;     ...
;         const bool has_next = sched_next(ui + 1, nM, nN, G, cblk, nxt);
;         const char* nA = has_next ? MP.a(nxt) : cA; const char* nB = has_next ? MP.b(nxt) : cB;
;         for (int t = 0; t < nt; t += 2) {
;             const bool last = (t == nt - 2);
;             const char* a1 = cA + (size_t)(t + 1) * kstep;
;             const char* a2 = last ? nA : cA + (size_t)(t + 2) * kstep; const char* b2 = last ? nB : cB + (size_t)(t + 2) * kstep;
;             const char* a3 = a2 + kstep; const char* b3 = b2 + kstep;
;             PG8_LDB(B0, 0, 0); PG8_SCHED; PG8_LDA(At, 0, 0); PG8_STAGE(PG8_SA(1, 1), a1 + hstepA, voffA);
;     ...
;         for (int a = 0; a < 2; ++a)
; #pragma unroll
;             for (int b = 0; b < 2; ++b)
; #pragma unroll
;                 for (int m = 0; m < 4; ++m)
; #pragma unroll
;                     for (int n = 0; n < 2; ++n) acc[a][b][m][n] = (f32x4){0.f, 0.f, 0.f, 0.f};
.LBB1_2482:
	s_ashr_i32 s23, s22, 31
	v_cmp_lt_i64_e32 vcc, s[24:25], v[180:181]
	s_lshl_b64 s[24:25], s[22:23], 20
	s_add_u32 s24, s33, s24
	s_addc_u32 s25, s34, s25
	s_and_b64 s[26:27], vcc, exec
	s_cselect_b32 s23, s25, s29
	s_cselect_b32 s58, s24, s28
	s_ashr_i32 s21, s20, 31
	s_lshl_b64 s[26:27], s[20:21], 20
	s_add_u32 s26, s35, s26
	s_addc_u32 s27, s36, s27
	s_and_b64 s[42:43], vcc, exec
	s_cselect_b32 s21, s27, s47
	s_cselect_b32 s59, s26, s46
	s_add_u32 vcc_lo, s46, 0x100
	s_addc_u32 vcc_hi, s47, 0
	s_add_u32 s42, s28, 0x80080
	v_mov_b32_e32 v0, 0
	s_addc_u32 s43, s29, 0
	s_mov_b32 s3, -2
	v_mov_b32_e32 v1, 0
	v_mov_b64_e32 v[2:3], 0
	v_mov_b64_e32 v[4:5], 0
	v_mov_b64_e32 v[6:7], 0
	v_mov_b64_e32 v[8:9], 0
	v_mov_b64_e32 v[10:11], 0
	v_mov_b64_e32 v[12:13], 0
	v_mov_b64_e32 v[14:15], 0
	v_mov_b64_e32 v[16:17], 0
	v_mov_b64_e32 v[18:19], 0
	v_mov_b64_e32 v[20:21], 0
	v_mov_b64_e32 v[22:23], 0
	v_mov_b64_e32 v[24:25], 0
	v_mov_b64_e32 v[26:27], 0
	v_mov_b64_e32 v[28:29], 0
	v_mov_b64_e32 v[30:31], 0
	v_mov_b64_e32 v[32:33], 0
	v_mov_b64_e32 v[34:35], 0
	v_mov_b64_e32 v[36:37], 0
	v_mov_b64_e32 v[38:39], 0
	v_mov_b64_e32 v[40:41], 0
	v_mov_b64_e32 v[42:43], 0
	v_mov_b64_e32 v[44:45], 0
	v_mov_b64_e32 v[46:47], 0
	v_mov_b64_e32 v[48:49], 0
	v_mov_b64_e32 v[50:51], 0
	v_mov_b64_e32 v[52:53], 0
	v_mov_b64_e32 v[54:55], 0
	v_mov_b64_e32 v[56:57], 0
	v_mov_b64_e32 v[58:59], 0
	v_mov_b64_e32 v[60:61], 0
	v_mov_b64_e32 v[62:63], 0
	v_mov_b64_e32 v[64:65], 0
	v_mov_b64_e32 v[66:67], 0
	v_mov_b64_e32 v[68:69], 0
	v_mov_b64_e32 v[70:71], 0
	v_mov_b64_e32 v[72:73], 0
	v_mov_b64_e32 v[74:75], 0
	v_mov_b64_e32 v[76:77], 0
	v_mov_b64_e32 v[78:79], 0
	v_mov_b64_e32 v[104:105], 0
	v_mov_b64_e32 v[106:107], 0
	v_mov_b64_e32 v[116:117], 0
	v_mov_b64_e32 v[118:119], 0
	v_mov_b64_e32 v[120:121], 0
	v_mov_b64_e32 v[122:123], 0
	v_mov_b64_e32 v[124:125], 0
	v_mov_b64_e32 v[126:127], 0
	v_mov_b64_e32 v[128:129], 0
	v_mov_b64_e32 v[130:131], 0
	v_mov_b64_e32 v[132:133], 0
	v_mov_b64_e32 v[134:135], 0
	v_mov_b64_e32 v[136:137], 0
	v_mov_b64_e32 v[138:139], 0
	v_mov_b64_e32 v[140:141], 0
	v_mov_b64_e32 v[142:143], 0
	v_mov_b64_e32 v[144:145], 0
	v_mov_b64_e32 v[146:147], 0
	v_mov_b64_e32 v[148:149], 0
	v_mov_b64_e32 v[150:151], 0
	v_mov_b64_e32 v[152:153], 0
	v_mov_b64_e32 v[154:155], 0
	v_mov_b64_e32 v[156:157], 0
	v_mov_b64_e32 v[158:159], 0
	ds_read_b128 v[80:83], v189
	ds_read_b128 v[84:87], v189 offset:1024
	ds_read_b128 v[88:91], v189 offset:2048
	ds_read_b128 v[92:95], v189 offset:3072

;     DI const char* a(const Unit& u) const { return (const char*)(A + (size_t)u.pm * BM * lda); }
;     DI const char* a(const Unit& u) const { return (const char*)(A + (size_t)u.pm * BM * 2048 + (u.pn >> 1) * 512); }
;     DI const char* a(const Unit& u) const { return (const char*)((u.pn < 12 ? A1 : A2) + (size_t)u.pm * BM * 512); }
; #define PG8_STAGE(bufoff, gbase, voff) do { _Pragma("unroll") for (int _i = 0; _i < 2; ++_i) \
;         __builtin_amdgcn_global_load_lds((const unsigned*)((const char*)(gbase) + (voff)[_i]), (LAS unsigned*)(lds + (bufoff) + ldsw + _i * 8192), 16, 0, 0); } while (0)
; #define PG8_LDA(dst, b, h) do { _Pragma("unroll") for (int m = 0; m < 4; ++m) _Pragma("unroll") for (int k = 0; k < 2; ++k) dst[m][k] = *(const LAS bf16x8*)(lds + PG8_SA(b, h) + aoff + m * 2048 + k * 1024); } while (0)
; #define PG8_LDB(dst, b, h) do { _Pragma("unroll") for (int n = 0; n < 2; ++n) _Pragma("unroll") for (int k = 0; k < 2; ++k) dst[n][k] = *(const LAS bf16x8*)(lds + PG8_SB(b, h) + boff + n * 2048 + k * 1024); } while (0)
; #define PG8_SCHED __builtin_amdgcn_sched_barrier(0)
; template <class Map, class Epi>
; DI void gemm_phase(LAS unsigned char* lds, const Map& MP, const Epi& E, const int nM, const int nN, const int K, const int lda, const int ldb) {
;     ...
;             const char* a1 = cA + (size_t)(t + 1) * kstep;
;             const char* a2 = last ? nA : cA + (size_t)(t + 2) * kstep; const char* b2 = last ? nB : cB + (size_t)(t + 2) * kstep;
;             const char* a3 = a2 + kstep; const char* b3 = b2 + kstep;
;             PG8_LDB(B0, 0, 0); PG8_SCHED; PG8_LDA(At, 0, 0); PG8_STAGE(PG8_SA(1, 1), a1 + hstepA, voffA);
;     ...
;         for (int a = 0; a < 2; ++a)
; #pragma unroll
;             for (int b = 0; b < 2; ++b)
; #pragma unroll
;                 for (int m = 0; m < 4; ++m)
; #pragma unroll
;                     for (int n = 0; n < 2; ++n) acc[a][b][m][n] = (f32x4){0.f, 0.f, 0.f, 0.f};
.LBB1_2652:
	s_add_u32 s38, s10, 0x100
	v_mov_b32_e32 v0, 0
	s_addc_u32 s39, s11, 0
	s_mov_b32 s48, -2
	v_mov_b32_e32 v1, 0
	v_mov_b64_e32 v[2:3], 0
	v_mov_b64_e32 v[4:5], 0
	v_mov_b64_e32 v[6:7], 0
	v_mov_b64_e32 v[8:9], 0
	v_mov_b64_e32 v[10:11], 0
	v_mov_b64_e32 v[12:13], 0
	v_mov_b64_e32 v[14:15], 0
	v_mov_b64_e32 v[16:17], 0
	v_mov_b64_e32 v[18:19], 0
	v_mov_b64_e32 v[20:21], 0
	v_mov_b64_e32 v[22:23], 0
	v_mov_b64_e32 v[24:25], 0
	v_mov_b64_e32 v[26:27], 0
	v_mov_b64_e32 v[28:29], 0
	v_mov_b64_e32 v[30:31], 0
	v_mov_b64_e32 v[32:33], 0
	v_mov_b64_e32 v[34:35], 0
	v_mov_b64_e32 v[36:37], 0
	v_mov_b64_e32 v[38:39], 0
	v_mov_b64_e32 v[40:41], 0
	v_mov_b64_e32 v[42:43], 0
	v_mov_b64_e32 v[44:45], 0
	v_mov_b64_e32 v[46:47], 0
	v_mov_b64_e32 v[48:49], 0
	v_mov_b64_e32 v[50:51], 0
	v_mov_b64_e32 v[52:53], 0
	v_mov_b64_e32 v[54:55], 0
	v_mov_b64_e32 v[56:57], 0
	v_mov_b64_e32 v[58:59], 0
	v_mov_b64_e32 v[60:61], 0
	v_mov_b64_e32 v[62:63], 0
	v_mov_b64_e32 v[64:65], 0
	v_mov_b64_e32 v[66:67], 0
	v_mov_b64_e32 v[68:69], 0
	v_mov_b64_e32 v[70:71], 0
	v_mov_b64_e32 v[72:73], 0
	v_mov_b64_e32 v[74:75], 0
	v_mov_b64_e32 v[76:77], 0
	v_mov_b64_e32 v[78:79], 0
	v_mov_b64_e32 v[80:81], 0
	v_mov_b64_e32 v[82:83], 0
	v_mov_b64_e32 v[84:85], 0
	v_mov_b64_e32 v[86:87], 0
	v_mov_b64_e32 v[88:89], 0
	v_mov_b64_e32 v[90:91], 0
	v_mov_b64_e32 v[92:93], 0
	v_mov_b64_e32 v[94:95], 0
	v_mov_b64_e32 v[96:97], 0
	v_mov_b64_e32 v[98:99], 0
	v_mov_b64_e32 v[100:101], 0
	v_mov_b64_e32 v[102:103], 0
	v_mov_b64_e32 v[104:105], 0
	v_mov_b64_e32 v[106:107], 0
	v_mov_b64_e32 v[108:109], 0
	v_mov_b64_e32 v[110:111], 0
	v_mov_b64_e32 v[112:113], 0
	v_mov_b64_e32 v[114:115], 0
	v_mov_b64_e32 v[116:117], 0
	v_mov_b64_e32 v[118:119], 0
	v_mov_b64_e32 v[120:121], 0
	v_mov_b64_e32 v[122:123], 0
	v_mov_b64_e32 v[124:125], 0
	v_mov_b64_e32 v[126:127], 0
	ds_read_b128 v[152:155], v149
	ds_read_b128 v[156:159], v149 offset:1024
	ds_read_b128 v[160:163], v149 offset:2048
	ds_read_b128 v[164:167], v149 offset:3072
